# attention steady loop: first QK MFMA issued immediately after the step barrier (row-sum adds retargeted off the MFMA destination); last-gap exps moved ahead of the last PV MFMA
# baseline (speedup 1.0000x reference)
.LBB0_1277:
	s_lshl_b32 s18, s23, 1
	v_mfma_f32_32x32x16_bf16 v[112:127], v[188:191], v[156:159], v[238:253]
	v_add_u32_e32 v237, s18, v214
	ds_read_b64_tr_b16 v[192:193], v237 offset:24576
	v_add_f32_e32 v128, v80, v81
	v_add_f32_e32 v128, v82, v128
	v_add_f32_e32 v128, v83, v128
	v_add_f32_e32 v128, v84, v128
	v_add_f32_e32 v128, v85, v128
	v_cvt_pk_bf16_f32 v148, v80, v81
	v_cvt_pk_bf16_f32 v149, v82, v83
	ds_read_b64_tr_b16 v[194:195], v237 offset:25088
	s_waitcnt lgkmcnt(8)
	v_mfma_f32_32x32x16_bf16 v[96:111], v[184:187], v[156:159], v[238:253]
	v_add_f32_e32 v80, v86, v128
	v_add_f32_e32 v80, v87, v80
	v_add_f32_e32 v80, v88, v80
	v_add_f32_e32 v82, v89, v80
	v_cvt_pk_bf16_f32 v150, v84, v85
	v_cvt_pk_bf16_f32 v151, v86, v87
	ds_read_b64_tr_b16 v[80:81], v237 offset:28672
	s_waitcnt lgkmcnt(8)
	v_mfma_f32_32x32x16_bf16 v[112:127], v[180:183], v[152:155], v[112:127]
	v_add_f32_e32 v82, v90, v82
	v_add_f32_e32 v82, v91, v82
	v_add_f32_e32 v82, v92, v82
	v_add_f32_e32 v84, v93, v82
	v_cvt_pk_bf16_f32 v140, v88, v89
	v_cvt_pk_bf16_f32 v141, v90, v91
	ds_read_b64_tr_b16 v[82:83], v237 offset:29184
	s_waitcnt lgkmcnt(8)
	v_mfma_f32_32x32x16_bf16 v[96:111], v[176:179], v[152:155], v[96:111]
	v_add_f32_e32 v84, v94, v84
	v_add_f32_e32 v84, v95, v84
	v_add_f32_e32 v84, v64, v84
	v_add_f32_e32 v86, v65, v84
	v_cvt_pk_bf16_f32 v142, v92, v93
	v_cvt_pk_bf16_f32 v143, v94, v95
	ds_read_b64_tr_b16 v[84:85], v237 offset:32768
	s_waitcnt lgkmcnt(8)
	v_mfma_f32_32x32x16_bf16 v[112:127], v[172:175], v[144:147], v[112:127]
	v_add_f32_e32 v86, v66, v86
	v_add_f32_e32 v86, v67, v86
	v_add_f32_e32 v86, v68, v86
	v_add_f32_e32 v88, v69, v86
	v_cvt_pk_bf16_f32 v132, v64, v65
	v_cvt_pk_bf16_f32 v133, v66, v67
	ds_read_b64_tr_b16 v[86:87], v237 offset:33280
	s_waitcnt lgkmcnt(8)
	v_mfma_f32_32x32x16_bf16 v[96:111], v[168:171], v[144:147], v[96:111]
	v_add_f32_e32 v64, v70, v88
	v_add_f32_e32 v64, v71, v64
	v_add_f32_e32 v64, v72, v64
	v_add_f32_e32 v66, v73, v64
	v_cvt_pk_bf16_f32 v134, v68, v69
	v_cvt_pk_bf16_f32 v135, v70, v71
	ds_read_b64_tr_b16 v[64:65], v237 offset:36864
	s_waitcnt lgkmcnt(8)
	v_mfma_f32_32x32x16_bf16 v[112:127], v[164:167], v[136:139], v[112:127]
	v_add_f32_e32 v66, v74, v66
	v_add_f32_e32 v66, v75, v66
	v_add_f32_e32 v66, v76, v66
	v_add_f32_e32 v68, v77, v66
	v_cvt_pk_bf16_f32 v128, v72, v73
	v_cvt_pk_bf16_f32 v129, v74, v75
	ds_read_b64_tr_b16 v[66:67], v237 offset:37376
	s_waitcnt lgkmcnt(8)
	v_mfma_f32_32x32x16_bf16 v[96:111], v[160:163], v[136:139], v[96:111]
	v_add_f32_e32 v68, v78, v68
	v_add_f32_e32 v68, v79, v68
	v_add_f32_e32 v236, v236, v68
	v_cvt_pk_bf16_f32 v130, v76, v77
	v_cvt_pk_bf16_f32 v131, v78, v79
	s_add_u32 s30, s98, 0xffffe000
	s_addc_u32 s31, s99, -1
	s_add_i32 s18, s86, s89
	s_nop 0
	s_mov_b32 s23, m0
	s_mov_b32 m0, s18
	s_nop 0
	global_load_lds_dwordx4 v196, s[30:31]
	s_mov_b32 m0, s23
	s_add_u32 s30, s100, 0xffffc000
	s_addc_u32 s31, s101, -1
	s_lshl_b32 s18, s37, 1
	s_add_i32 s18, s18, s90
	s_mov_b32 s23, m0
	s_mov_b32 m0, s18
	s_nop 0
	global_load_lds_dwordx4 v196, s[30:31]
	s_mov_b32 m0, s23
	s_add_u32 s30, s100, 0xffffe000
	s_addc_u32 s31, s101, -1
	s_addk_i32 s18, 0x2000
	s_mov_b32 s23, m0
	s_mov_b32 m0, s18
	s_nop 0
	global_load_lds_dwordx4 v196, s[30:31]
	s_mov_b32 m0, s23
	v_max_f32_e32 v68, v113, v112
	v_max3_f32 v69, v114, v115, v97
	v_max3_f32 v68, v68, v96, v98
	v_max3_f32 v68, v68, v99, v116
	v_max3_f32 v69, v69, v118, v119
	v_max3_f32 v68, v68, v117, v100
	v_max3_f32 v69, v69, v102, v103
	v_max3_f32 v68, v68, v101, v120
	v_max3_f32 v69, v69, v122, v123
	v_max3_f32 v68, v68, v121, v104
	v_max3_f32 v69, v69, v106, v107
	v_max3_f32 v68, v68, v105, v124
	v_max3_f32 v69, v69, v126, v127
	v_max3_f32 v68, v68, v125, v108
	v_max3_f32 v69, v69, v110, v111
	v_max3_f32 v68, v68, v109, v69
	v_cmp_lt_f32_e32 vcc, s71, v68
	s_cmp_lg_u64 vcc, 0
	s_cselect_b64 s[50:51], -1, 0
	s_cbranch_vccnz .LBB0_1285
.LBB0_1278:
	ds_read_b64_tr_b16 v[68:69], v237 offset:25600
	ds_read_b64_tr_b16 v[70:71], v237 offset:26112
	s_waitcnt lgkmcnt(8)
	v_mfma_f32_32x32x16_bf16 v[32:47], v[148:151], v[192:195], v[32:47]
	v_exp_f32_e32 v112, v112
	v_exp_f32_e32 v113, v113
	ds_read_b64_tr_b16 v[72:73], v237 offset:29696
	ds_read_b64_tr_b16 v[74:75], v237 offset:30208
	s_waitcnt lgkmcnt(8)
	v_mfma_f32_32x32x16_bf16 v[48:63], v[148:151], v[80:83], v[48:63]
	v_exp_f32_e32 v114, v114
	v_exp_f32_e32 v115, v115
	ds_read_b64_tr_b16 v[76:77], v237 offset:33792
	ds_read_b64_tr_b16 v[78:79], v237 offset:34304
	s_waitcnt lgkmcnt(8)
	v_mfma_f32_32x32x16_bf16 v[16:31], v[148:151], v[84:87], v[16:31]
	v_exp_f32_e32 v116, v116
	v_exp_f32_e32 v117, v117
	ds_read_b64_tr_b16 v[80:81], v237 offset:37888
	ds_read_b64_tr_b16 v[82:83], v237 offset:38400
	s_waitcnt lgkmcnt(8)
	v_mfma_f32_32x32x16_bf16 v[0:15], v[148:151], v[64:67], v[0:15]
	v_exp_f32_e32 v118, v118
	v_exp_f32_e32 v119, v119
	ds_read_b64_tr_b16 v[64:65], v237 offset:26624
	ds_read_b64_tr_b16 v[66:67], v237 offset:27136
	s_waitcnt lgkmcnt(8)
	v_mfma_f32_32x32x16_bf16 v[32:47], v[140:143], v[68:71], v[32:47]
	v_exp_f32_e32 v120, v120
	v_exp_f32_e32 v121, v121
	ds_read_b64_tr_b16 v[68:69], v237 offset:30720
	ds_read_b64_tr_b16 v[70:71], v237 offset:31232
	s_waitcnt lgkmcnt(8)
	v_mfma_f32_32x32x16_bf16 v[48:63], v[140:143], v[72:75], v[48:63]
	v_exp_f32_e32 v122, v122
	v_exp_f32_e32 v123, v123
	ds_read_b64_tr_b16 v[72:73], v237 offset:34816
	ds_read_b64_tr_b16 v[74:75], v237 offset:35328
	s_waitcnt lgkmcnt(8)
	v_mfma_f32_32x32x16_bf16 v[16:31], v[140:143], v[76:79], v[16:31]
	v_exp_f32_e32 v124, v124
	v_exp_f32_e32 v125, v125
	ds_read_b64_tr_b16 v[76:77], v237 offset:38912
	ds_read_b64_tr_b16 v[78:79], v237 offset:39424
	s_waitcnt lgkmcnt(8)
; #define WAIT_BAR(N) asm volatile("s_waitcnt vmcnt(" #N ") lgkmcnt(0)\n\ts_barrier":::"memory")
;   #define RESC() do{ if(resc){ asm volatile("s_waitcnt lgkmcnt(0)":::"memory"); \
;       _Pragma("unroll") for(int d_=0;d_<4;++d_) _Pragma("unroll") for(int r=0;r<16;++r)o[d_][r]*=wsf[crow(r,hi)]; } }while(0)
;   #define ROT() do{sl_prev=sl_cur;sl_cur=sl_next;sl_next=(sl_next==(NSLOT-1)*SLOTB)?0:sl_next+SLOTB;}while(0)
; template<int THRL> __device__ __forceinline__ void attn_unit(int b,int hc,int qb,const bf16*Q,const bf16*__restrict__ K,const bf16*__restrict__ V,bf16*O,char*shm){
;     ...
;     STEP(pB0,pB1,pA0,pA1,t,true,true,true);     WAIT_BAR(3); RESC(); ROT();
	v_mfma_f32_32x32x16_bf16 v[0:15], v[140:143], v[80:83], v[0:15]
	v_exp_f32_e32 v126, v126
	v_exp_f32_e32 v127, v127
	ds_read_b64_tr_b16 v[80:81], v237 offset:27648
	ds_read_b64_tr_b16 v[82:83], v237 offset:28160
	s_waitcnt lgkmcnt(8)
	v_mfma_f32_32x32x16_bf16 v[32:47], v[132:135], v[64:67], v[32:47]
	v_exp_f32_e32 v96, v96
	v_exp_f32_e32 v97, v97
	ds_read_b64_tr_b16 v[64:65], v237 offset:31744
	ds_read_b64_tr_b16 v[66:67], v237 offset:32256
	s_waitcnt lgkmcnt(8)
	v_mfma_f32_32x32x16_bf16 v[48:63], v[132:135], v[68:71], v[48:63]
	v_exp_f32_e32 v98, v98
	v_exp_f32_e32 v99, v99
	ds_read_b64_tr_b16 v[68:69], v237 offset:35840
	ds_read_b64_tr_b16 v[70:71], v237 offset:36352
	s_waitcnt lgkmcnt(8)
	v_mfma_f32_32x32x16_bf16 v[16:31], v[132:135], v[72:75], v[16:31]
	v_exp_f32_e32 v100, v100
	v_exp_f32_e32 v101, v101
	ds_read_b64_tr_b16 v[72:73], v237 offset:39936
	ds_read_b64_tr_b16 v[74:75], v237 offset:40448
	s_waitcnt lgkmcnt(8)
	v_mfma_f32_32x32x16_bf16 v[0:15], v[132:135], v[76:79], v[0:15]
	v_exp_f32_e32 v102, v102
	v_exp_f32_e32 v103, v103
	v_add_u32_e32 v76, s37, v213
	ds_read_b128 v[192:195], v76
	ds_read_b128 v[188:191], v76 offset:512
	s_waitcnt lgkmcnt(8)
	v_mfma_f32_32x32x16_bf16 v[32:47], v[128:131], v[80:83], v[32:47]
	v_exp_f32_e32 v104, v104
	v_exp_f32_e32 v105, v105
	ds_read_b128 v[184:187], v76 offset:2048
	ds_read_b128 v[176:179], v76 offset:2560
	s_waitcnt lgkmcnt(8)
	v_mfma_f32_32x32x16_bf16 v[48:63], v[128:131], v[64:67], v[48:63]
	v_exp_f32_e32 v106, v106
	v_exp_f32_e32 v107, v107
	ds_read_b128 v[172:175], v76 offset:4096
	ds_read_b128 v[168:171], v76 offset:4608
	s_waitcnt lgkmcnt(8)
	v_mfma_f32_32x32x16_bf16 v[16:31], v[128:131], v[68:71], v[16:31]
	v_exp_f32_e32 v108, v108
	v_exp_f32_e32 v109, v109
	ds_read_b128 v[164:167], v76 offset:6144
	ds_read_b128 v[160:163], v76 offset:6656
	v_exp_f32_e32 v110, v110
	v_exp_f32_e32 v111, v111
	s_waitcnt lgkmcnt(8)
	v_mfma_f32_32x32x16_bf16 v[0:15], v[128:131], v[72:75], v[0:15]
	s_waitcnt vmcnt(3) lgkmcnt(0)
	s_barrier
	s_andn2_b64 vcc, exec, s[50:51]
	s_cbranch_vccnz .LBB0_1280
	s_waitcnt lgkmcnt(0)
	v_add_u32_e32 v76, s49, v216
	ds_read_b128 v[64:67], v76 offset:96
	ds_read_b128 v[68:71], v76 offset:64
	ds_read_b128 v[72:75], v76 offset:32
	ds_read_b128 v[76:79], v76
	s_waitcnt lgkmcnt(3)
	v_pk_mul_f32 v[44:45], v[44:45], v[64:65]
	s_waitcnt lgkmcnt(2)
	v_pk_mul_f32 v[40:41], v[40:41], v[68:69]
	s_waitcnt lgkmcnt(1)
	v_pk_mul_f32 v[36:37], v[36:37], v[72:73]
	v_pk_mul_f32 v[46:47], v[46:47], v[66:67]
	v_pk_mul_f32 v[42:43], v[42:43], v[70:71]
	v_pk_mul_f32 v[38:39], v[38:39], v[74:75]
	s_waitcnt lgkmcnt(0)
	v_pk_mul_f32 v[34:35], v[34:35], v[78:79]
	v_pk_mul_f32 v[32:33], v[32:33], v[76:77]
	v_pk_mul_f32 v[60:61], v[60:61], v[64:65]
	v_pk_mul_f32 v[56:57], v[56:57], v[68:69]
	v_pk_mul_f32 v[52:53], v[52:53], v[72:73]
	v_pk_mul_f32 v[62:63], v[62:63], v[66:67]
	v_pk_mul_f32 v[58:59], v[58:59], v[70:71]
	v_pk_mul_f32 v[54:55], v[54:55], v[74:75]
	v_pk_mul_f32 v[50:51], v[50:51], v[78:79]
	v_pk_mul_f32 v[48:49], v[48:49], v[76:77]
	v_pk_mul_f32 v[28:29], v[28:29], v[64:65]
	v_pk_mul_f32 v[24:25], v[24:25], v[68:69]
	v_pk_mul_f32 v[20:21], v[20:21], v[72:73]
	v_pk_mul_f32 v[30:31], v[30:31], v[66:67]
	v_pk_mul_f32 v[26:27], v[26:27], v[70:71]
	v_pk_mul_f32 v[22:23], v[22:23], v[74:75]
	v_pk_mul_f32 v[18:19], v[18:19], v[78:79]
	v_pk_mul_f32 v[16:17], v[16:17], v[76:77]
	v_pk_mul_f32 v[12:13], v[12:13], v[64:65]
	v_pk_mul_f32 v[8:9], v[8:9], v[68:69]
	v_pk_mul_f32 v[4:5], v[4:5], v[72:73]
	v_pk_mul_f32 v[14:15], v[14:15], v[66:67]
	v_pk_mul_f32 v[10:11], v[10:11], v[70:71]
	v_pk_mul_f32 v[6:7], v[6:7], v[74:75]
	v_pk_mul_f32 v[2:3], v[2:3], v[78:79]
	v_pk_mul_f32 v[0:1], v[0:1], v[76:77]
.LBB0_1280:
	s_add_i32 s18, s37, 0x2000
	s_lshl_b32 s23, s86, 1
	v_mfma_f32_32x32x16_bf16 v[80:95], v[192:195], v[156:159], v[238:253]
	v_add_u32_e32 v237, s23, v214
	ds_read_b64_tr_b16 v[180:181], v237 offset:24576
	s_cmpk_lg_i32 s37, 0x4000
	s_cselect_b32 s86, s18, 0
	v_add_f32_e32 v128, v112, v113
	v_add_f32_e32 v128, v114, v128
	v_add_f32_e32 v128, v115, v128
	v_add_f32_e32 v128, v116, v128
	v_add_f32_e32 v128, v117, v128
	v_cvt_pk_bf16_f32 v148, v112, v113
	v_cvt_pk_bf16_f32 v149, v114, v115
	ds_read_b64_tr_b16 v[182:183], v237 offset:25088
	s_waitcnt lgkmcnt(8)
	v_mfma_f32_32x32x16_bf16 v[64:79], v[188:191], v[156:159], v[238:253]
	v_add_f32_e32 v112, v118, v128
	v_add_f32_e32 v112, v119, v112
	v_add_f32_e32 v112, v120, v112
	v_add_f32_e32 v114, v121, v112
	v_cvt_pk_bf16_f32 v150, v116, v117
	v_cvt_pk_bf16_f32 v151, v118, v119
	ds_read_b64_tr_b16 v[112:113], v237 offset:28672
	s_waitcnt lgkmcnt(8)
	v_mfma_f32_32x32x16_bf16 v[80:95], v[184:187], v[152:155], v[80:95]
	v_add_f32_e32 v114, v122, v114
	v_add_f32_e32 v114, v123, v114
	v_add_f32_e32 v114, v124, v114
	v_add_f32_e32 v116, v125, v114
	v_cvt_pk_bf16_f32 v140, v120, v121
	v_cvt_pk_bf16_f32 v141, v122, v123
	ds_read_b64_tr_b16 v[114:115], v237 offset:29184
	s_waitcnt lgkmcnt(8)
	v_mfma_f32_32x32x16_bf16 v[64:79], v[176:179], v[152:155], v[64:79]
	v_add_f32_e32 v116, v126, v116
	v_add_f32_e32 v116, v127, v116
	v_add_f32_e32 v116, v96, v116
	v_add_f32_e32 v118, v97, v116
	v_cvt_pk_bf16_f32 v142, v124, v125
	v_cvt_pk_bf16_f32 v143, v126, v127
	ds_read_b64_tr_b16 v[116:117], v237 offset:32768
	s_waitcnt lgkmcnt(8)
	v_mfma_f32_32x32x16_bf16 v[80:95], v[172:175], v[144:147], v[80:95]
	v_add_f32_e32 v118, v98, v118
	v_add_f32_e32 v118, v99, v118
	v_add_f32_e32 v118, v100, v118
	v_add_f32_e32 v120, v101, v118
	v_cvt_pk_bf16_f32 v132, v96, v97
	v_cvt_pk_bf16_f32 v133, v98, v99
	ds_read_b64_tr_b16 v[118:119], v237 offset:33280
	s_waitcnt lgkmcnt(8)
	v_mfma_f32_32x32x16_bf16 v[64:79], v[168:171], v[144:147], v[64:79]
	v_add_f32_e32 v96, v102, v120
	v_add_f32_e32 v96, v103, v96
	v_add_f32_e32 v96, v104, v96
	v_add_f32_e32 v98, v105, v96
	v_cvt_pk_bf16_f32 v134, v100, v101
	v_cvt_pk_bf16_f32 v135, v102, v103
	ds_read_b64_tr_b16 v[96:97], v237 offset:36864
	s_waitcnt lgkmcnt(8)
	v_mfma_f32_32x32x16_bf16 v[80:95], v[164:167], v[136:139], v[80:95]
	v_add_f32_e32 v98, v106, v98
	v_add_f32_e32 v98, v107, v98
	v_add_f32_e32 v98, v108, v98
	v_add_f32_e32 v100, v109, v98
	v_cvt_pk_bf16_f32 v128, v104, v105
	v_cvt_pk_bf16_f32 v129, v106, v107
	ds_read_b64_tr_b16 v[98:99], v237 offset:37376
	s_waitcnt lgkmcnt(8)
	v_mfma_f32_32x32x16_bf16 v[64:79], v[160:163], v[136:139], v[64:79]
	v_add_f32_e32 v100, v110, v100
	v_add_f32_e32 v100, v111, v100
	v_add_f32_e32 v236, v236, v100
	v_cvt_pk_bf16_f32 v130, v108, v109
	v_cvt_pk_bf16_f32 v131, v110, v111
	s_add_i32 s18, s37, s89
	s_mov_b32 s23, m0
	s_mov_b32 m0, s18
	s_nop 0
	global_load_lds_dwordx4 v196, s[98:99]
	s_mov_b32 m0, s23
	s_lshl_b32 s18, s86, 1
	s_add_i32 s18, s18, s90
	s_mov_b32 s23, m0
	s_mov_b32 m0, s18
	s_nop 0
	global_load_lds_dwordx4 v196, s[100:101]
	s_mov_b32 m0, s23
	s_add_u32 s30, s100, 0x2000
	s_addc_u32 s31, s101, 0
	s_addk_i32 s18, 0x2000
	s_mov_b32 s23, m0
	s_mov_b32 m0, s18
	s_nop 0
	global_load_lds_dwordx4 v196, s[30:31]
	s_mov_b32 m0, s23
	v_max_f32_e32 v100, v81, v80
	v_max3_f32 v101, v82, v83, v65
	v_max3_f32 v100, v100, v64, v66
	v_max3_f32 v100, v100, v67, v84
	v_max3_f32 v101, v101, v86, v87
	v_max3_f32 v100, v100, v85, v68
	v_max3_f32 v101, v101, v70, v71
	v_max3_f32 v100, v100, v69, v88
	v_max3_f32 v101, v101, v90, v91
	v_max3_f32 v100, v100, v89, v72
	v_max3_f32 v101, v101, v74, v75
	v_max3_f32 v100, v100, v73, v92
	v_max3_f32 v101, v101, v94, v95
	v_max3_f32 v100, v100, v93, v76
	v_max3_f32 v101, v101, v78, v79
	v_max3_f32 v100, v100, v77, v101
	v_cmp_lt_f32_e32 vcc, s71, v100
	s_cmp_lg_u64 vcc, 0
	s_cselect_b64 s[50:51], -1, 0
	s_cbranch_vccnz .LBB0_1288
.LBB0_1281:
	ds_read_b64_tr_b16 v[100:101], v237 offset:25600
	ds_read_b64_tr_b16 v[102:103], v237 offset:26112
	s_waitcnt lgkmcnt(8)
	v_mfma_f32_32x32x16_bf16 v[32:47], v[148:151], v[180:183], v[32:47]
	v_exp_f32_e32 v80, v80
	v_exp_f32_e32 v81, v81
	ds_read_b64_tr_b16 v[104:105], v237 offset:29696
	ds_read_b64_tr_b16 v[106:107], v237 offset:30208
	s_waitcnt lgkmcnt(8)
	v_mfma_f32_32x32x16_bf16 v[48:63], v[148:151], v[112:115], v[48:63]
	v_exp_f32_e32 v82, v82
	v_exp_f32_e32 v83, v83
	ds_read_b64_tr_b16 v[108:109], v237 offset:33792
	ds_read_b64_tr_b16 v[110:111], v237 offset:34304
	s_waitcnt lgkmcnt(8)
	v_mfma_f32_32x32x16_bf16 v[16:31], v[148:151], v[116:119], v[16:31]
	v_exp_f32_e32 v84, v84
	v_exp_f32_e32 v85, v85
	ds_read_b64_tr_b16 v[112:113], v237 offset:37888
	ds_read_b64_tr_b16 v[114:115], v237 offset:38400
	s_waitcnt lgkmcnt(8)
	v_mfma_f32_32x32x16_bf16 v[0:15], v[148:151], v[96:99], v[0:15]
	v_exp_f32_e32 v86, v86
	v_exp_f32_e32 v87, v87
	ds_read_b64_tr_b16 v[96:97], v237 offset:26624
	ds_read_b64_tr_b16 v[98:99], v237 offset:27136
	s_waitcnt lgkmcnt(8)
	v_mfma_f32_32x32x16_bf16 v[32:47], v[140:143], v[100:103], v[32:47]
	v_exp_f32_e32 v88, v88
	v_exp_f32_e32 v89, v89
	ds_read_b64_tr_b16 v[100:101], v237 offset:30720
	ds_read_b64_tr_b16 v[102:103], v237 offset:31232
	s_waitcnt lgkmcnt(8)
	v_mfma_f32_32x32x16_bf16 v[48:63], v[140:143], v[104:107], v[48:63]
	v_exp_f32_e32 v90, v90
	v_exp_f32_e32 v91, v91
	ds_read_b64_tr_b16 v[104:105], v237 offset:34816
	ds_read_b64_tr_b16 v[106:107], v237 offset:35328
	s_waitcnt lgkmcnt(8)
	v_mfma_f32_32x32x16_bf16 v[16:31], v[140:143], v[108:111], v[16:31]
	v_exp_f32_e32 v92, v92
	v_exp_f32_e32 v93, v93
	ds_read_b64_tr_b16 v[108:109], v237 offset:38912
	ds_read_b64_tr_b16 v[110:111], v237 offset:39424
	s_waitcnt lgkmcnt(8)
	v_mfma_f32_32x32x16_bf16 v[0:15], v[140:143], v[112:115], v[0:15]
	v_exp_f32_e32 v94, v94
	v_exp_f32_e32 v95, v95
	ds_read_b64_tr_b16 v[112:113], v237 offset:27648
	ds_read_b64_tr_b16 v[114:115], v237 offset:28160
	s_waitcnt lgkmcnt(8)
	v_mfma_f32_32x32x16_bf16 v[32:47], v[132:135], v[96:99], v[32:47]
	v_exp_f32_e32 v64, v64
	v_exp_f32_e32 v65, v65
	ds_read_b64_tr_b16 v[96:97], v237 offset:31744
	ds_read_b64_tr_b16 v[98:99], v237 offset:32256
	s_waitcnt lgkmcnt(8)
	v_mfma_f32_32x32x16_bf16 v[48:63], v[132:135], v[100:103], v[48:63]
	v_exp_f32_e32 v66, v66
	v_exp_f32_e32 v67, v67
	ds_read_b64_tr_b16 v[100:101], v237 offset:35840
	ds_read_b64_tr_b16 v[102:103], v237 offset:36352
	s_waitcnt lgkmcnt(8)
	v_mfma_f32_32x32x16_bf16 v[16:31], v[132:135], v[104:107], v[16:31]
	v_exp_f32_e32 v68, v68
	v_exp_f32_e32 v69, v69
	ds_read_b64_tr_b16 v[104:105], v237 offset:39936
	ds_read_b64_tr_b16 v[106:107], v237 offset:40448
	s_waitcnt lgkmcnt(8)
	v_mfma_f32_32x32x16_bf16 v[0:15], v[132:135], v[108:111], v[0:15]
	v_exp_f32_e32 v70, v70
	v_exp_f32_e32 v71, v71
	v_add_u32_e32 v108, s86, v213
	ds_read_b128 v[188:191], v108
	ds_read_b128 v[184:187], v108 offset:512
	s_waitcnt lgkmcnt(8)
	v_mfma_f32_32x32x16_bf16 v[32:47], v[128:131], v[112:115], v[32:47]
	v_exp_f32_e32 v72, v72
	v_exp_f32_e32 v73, v73
	ds_read_b128 v[180:183], v108 offset:2048
	ds_read_b128 v[176:179], v108 offset:2560
	s_waitcnt lgkmcnt(8)
	v_mfma_f32_32x32x16_bf16 v[48:63], v[128:131], v[96:99], v[48:63]
	v_exp_f32_e32 v74, v74
	v_exp_f32_e32 v75, v75
	ds_read_b128 v[172:175], v108 offset:4096
	ds_read_b128 v[168:171], v108 offset:4608
	s_waitcnt lgkmcnt(8)
	v_mfma_f32_32x32x16_bf16 v[16:31], v[128:131], v[100:103], v[16:31]
	v_exp_f32_e32 v76, v76
	v_exp_f32_e32 v77, v77
	ds_read_b128 v[164:167], v108 offset:6144
	ds_read_b128 v[160:163], v108 offset:6656
	v_exp_f32_e32 v78, v78
	v_exp_f32_e32 v79, v79
	s_waitcnt lgkmcnt(8)
	v_mfma_f32_32x32x16_bf16 v[0:15], v[128:131], v[104:107], v[0:15]
	s_waitcnt vmcnt(3) lgkmcnt(0)
	s_barrier
	s_andn2_b64 vcc, exec, s[50:51]
	s_cbranch_vccnz .LBB0_1283
	s_waitcnt lgkmcnt(0)
	v_add_u32_e32 v108, s49, v216
	ds_read_b128 v[96:99], v108 offset:96
	ds_read_b128 v[100:103], v108 offset:64
	ds_read_b128 v[104:107], v108 offset:32
	ds_read_b128 v[108:111], v108
	s_waitcnt lgkmcnt(3)
	v_pk_mul_f32 v[44:45], v[44:45], v[96:97]
	s_waitcnt lgkmcnt(2)
	v_pk_mul_f32 v[40:41], v[40:41], v[100:101]
	s_waitcnt lgkmcnt(1)
	v_pk_mul_f32 v[36:37], v[36:37], v[104:105]
	v_pk_mul_f32 v[46:47], v[46:47], v[98:99]
	v_pk_mul_f32 v[42:43], v[42:43], v[102:103]
	v_pk_mul_f32 v[38:39], v[38:39], v[106:107]
	s_waitcnt lgkmcnt(0)
	v_pk_mul_f32 v[34:35], v[34:35], v[110:111]
	v_pk_mul_f32 v[32:33], v[32:33], v[108:109]
	v_pk_mul_f32 v[60:61], v[60:61], v[96:97]
	v_pk_mul_f32 v[56:57], v[56:57], v[100:101]
	v_pk_mul_f32 v[52:53], v[52:53], v[104:105]
	v_pk_mul_f32 v[62:63], v[62:63], v[98:99]
	v_pk_mul_f32 v[58:59], v[58:59], v[102:103]
	v_pk_mul_f32 v[54:55], v[54:55], v[106:107]
	v_pk_mul_f32 v[50:51], v[50:51], v[110:111]
	v_pk_mul_f32 v[48:49], v[48:49], v[108:109]
	v_pk_mul_f32 v[28:29], v[28:29], v[96:97]
	v_pk_mul_f32 v[24:25], v[24:25], v[100:101]
	v_pk_mul_f32 v[20:21], v[20:21], v[104:105]
	v_pk_mul_f32 v[30:31], v[30:31], v[98:99]
	v_pk_mul_f32 v[26:27], v[26:27], v[102:103]
	v_pk_mul_f32 v[22:23], v[22:23], v[106:107]
	v_pk_mul_f32 v[18:19], v[18:19], v[110:111]
	v_pk_mul_f32 v[16:17], v[16:17], v[108:109]
	v_pk_mul_f32 v[12:13], v[12:13], v[96:97]
	v_pk_mul_f32 v[8:9], v[8:9], v[100:101]
	v_pk_mul_f32 v[4:5], v[4:5], v[104:105]
	v_pk_mul_f32 v[14:15], v[14:15], v[98:99]
	v_pk_mul_f32 v[10:11], v[10:11], v[102:103]
	v_pk_mul_f32 v[6:7], v[6:7], v[106:107]
	v_pk_mul_f32 v[2:3], v[2:3], v[110:111]
	v_pk_mul_f32 v[0:1], v[0:1], v[108:109]
